# QK ring: each K fragment refilled right after the MFMA that consumed it (1 MFMA : 1 read interleave)
# baseline (speedup 1.0000x reference)
.LBB0_513:
	s_lshl_b32 s4, s76, 14
	v_add3_u32 v236, s4, v221, v220
	ds_read_b128 v[192:195], v236
	ds_read_b128 v[196:199], v236 offset:8192
	v_add3_u32 v236, s4, v222, v220
	ds_read_b128 v[200:203], v236
	ds_read_b128 v[204:207], v236 offset:8192
	v_add3_u32 v236, s4, v223, v220
	ds_read_b128 v[240:243], v236
	ds_read_b128 v[244:247], v236 offset:8192
	v_add3_u32 v236, s4, v224, v220
	ds_read_b128 v[248:251], v236
	ds_read_b128 v[252:255], v236 offset:8192
	s_waitcnt lgkmcnt(7)
	v_mfma_f32_32x32x16_bf16 v[144:159], v[192:195], v[160:163], 0
	v_add3_u32 v236, s4, v225, v220
	ds_read_b128 v[192:195], v236
	s_waitcnt lgkmcnt(7)
	v_mfma_f32_32x32x16_bf16 v[128:143], v[196:199], v[160:163], 0
	ds_read_b128 v[196:199], v236 offset:8192
	s_waitcnt lgkmcnt(7)
	v_mfma_f32_32x32x16_bf16 v[144:159], v[200:203], v[164:167], v[144:159]
	v_add3_u32 v236, s4, v227, v220
	ds_read_b128 v[200:203], v236
	s_waitcnt lgkmcnt(7)
	v_mfma_f32_32x32x16_bf16 v[128:143], v[204:207], v[164:167], v[128:143]
	ds_read_b128 v[204:207], v236 offset:8192
	s_waitcnt lgkmcnt(7)
	v_mfma_f32_32x32x16_bf16 v[144:159], v[240:243], v[168:171], v[144:159]
	v_add3_u32 v236, s4, v228, v220
	ds_read_b128 v[240:243], v236
	s_waitcnt lgkmcnt(7)
	v_mfma_f32_32x32x16_bf16 v[128:143], v[244:247], v[168:171], v[128:143]
	ds_read_b128 v[244:247], v236 offset:8192
	s_waitcnt lgkmcnt(7)
	v_mfma_f32_32x32x16_bf16 v[144:159], v[248:251], v[172:175], v[144:159]
	v_add3_u32 v236, s4, v229, v220
	ds_read_b128 v[248:251], v236
	s_waitcnt lgkmcnt(7)
	v_mfma_f32_32x32x16_bf16 v[128:143], v[252:255], v[172:175], v[128:143]
	ds_read_b128 v[252:255], v236 offset:8192
	s_waitcnt lgkmcnt(7)
	v_mfma_f32_32x32x16_bf16 v[144:159], v[192:195], v[176:179], v[144:159]
	s_waitcnt lgkmcnt(6)
	v_mfma_f32_32x32x16_bf16 v[128:143], v[196:199], v[176:179], v[128:143]
	s_waitcnt lgkmcnt(5)
	v_mfma_f32_32x32x16_bf16 v[144:159], v[200:203], v[180:183], v[144:159]
	s_waitcnt lgkmcnt(4)
	v_mfma_f32_32x32x16_bf16 v[128:143], v[204:207], v[180:183], v[128:143]
	s_waitcnt lgkmcnt(3)
	v_mfma_f32_32x32x16_bf16 v[144:159], v[240:243], v[184:187], v[144:159]
	s_waitcnt lgkmcnt(2)
	v_mfma_f32_32x32x16_bf16 v[128:143], v[244:247], v[184:187], v[128:143]
	s_waitcnt lgkmcnt(1)
	v_mfma_f32_32x32x16_bf16 v[144:159], v[248:251], v[188:191], v[144:159]
	s_waitcnt lgkmcnt(0)
	v_mfma_f32_32x32x16_bf16 v[128:143], v[252:255], v[188:191], v[128:143]
	s_nop 9
	v_max_f32_e32 v192, v144, v145
	v_max3_f32 v192, v192, v146, v147
	v_max3_f32 v192, v192, v148, v149
	v_max3_f32 v192, v192, v150, v151
	v_max3_f32 v192, v192, v152, v153
	v_max3_f32 v192, v192, v154, v155
	v_max3_f32 v192, v192, v156, v157
	v_max3_f32 v192, v192, v158, v159
	v_max3_f32 v192, v192, v128, v129
	v_max3_f32 v192, v192, v130, v131
	v_max3_f32 v192, v192, v132, v133
	v_max3_f32 v192, v192, v134, v135
	v_max3_f32 v192, v192, v136, v137
	v_max3_f32 v192, v192, v138, v139
	v_max3_f32 v192, v192, v140, v141
	v_max3_f32 v192, v192, v142, v143
	v_mov_b32_e32 v193, v192
	s_nop 1
	v_permlane32_swap_b32_e32 v192, v193
	v_max_f32_e32 v192, v192, v193
	v_sub_f32_e32 v193, v192, v231
	v_cmp_ge_f32_e32 vcc, s38, v193
	v_max_f32_e32 v234, v231, v192
	v_sub_f32_e32 v192, v231, v234
	v_mul_f32_e32 v192, 0x3e0293ee, v192
	v_exp_f32_e32 v192, v192
	s_cmp_eq_u64 vcc, exec
	s_cselect_b64 s[4:5], -1, 0
	v_cndmask_b32_e64 v233, v192, 1.0, s[4:5]
	v_cmp_gt_f32_e32 vcc, 1.0, v233
	s_cbranch_vccz .LBB0_517
	s_and_saveexec_b64 s[24:25], s[0:1]
	ds_write_b32 v226, v233 offset:128
	s_or_b64 exec, exec, s[24:25]
	s_waitcnt lgkmcnt(0)
	v_add_u32_e32 v192, s21, v210
	ds_read_b128 v[204:207], v192 offset:224
	ds_read_b128 v[200:203], v192 offset:192
	ds_read_b128 v[196:199], v192 offset:160
	ds_read_b128 v[192:195], v192 offset:128
	s_waitcnt lgkmcnt(3)
	v_pk_mul_f32 v[12:13], v[12:13], v[204:205]
	s_waitcnt lgkmcnt(2)
	v_pk_mul_f32 v[8:9], v[8:9], v[200:201]
	s_waitcnt lgkmcnt(1)
	v_pk_mul_f32 v[4:5], v[4:5], v[196:197]
	v_pk_mul_f32 v[14:15], v[14:15], v[206:207]
	v_pk_mul_f32 v[10:11], v[10:11], v[202:203]
	v_pk_mul_f32 v[6:7], v[6:7], v[198:199]
	s_waitcnt lgkmcnt(0)
	v_pk_mul_f32 v[2:3], v[2:3], v[194:195]
	v_pk_mul_f32 v[0:1], v[0:1], v[192:193]
	v_pk_mul_f32 v[124:125], v[124:125], v[204:205]
	v_pk_mul_f32 v[120:121], v[120:121], v[200:201]
	v_pk_mul_f32 v[116:117], v[116:117], v[196:197]
	v_pk_mul_f32 v[126:127], v[126:127], v[206:207]
	v_pk_mul_f32 v[122:123], v[122:123], v[202:203]
	v_pk_mul_f32 v[118:119], v[118:119], v[198:199]
	v_pk_mul_f32 v[114:115], v[114:115], v[194:195]
	v_pk_mul_f32 v[112:113], v[112:113], v[192:193]
	v_pk_mul_f32 v[108:109], v[108:109], v[204:205]
	v_pk_mul_f32 v[104:105], v[104:105], v[200:201]
	v_pk_mul_f32 v[100:101], v[100:101], v[196:197]
	v_pk_mul_f32 v[110:111], v[110:111], v[206:207]
	v_pk_mul_f32 v[106:107], v[106:107], v[202:203]
	v_pk_mul_f32 v[102:103], v[102:103], v[198:199]
	v_pk_mul_f32 v[98:99], v[98:99], v[194:195]
	v_pk_mul_f32 v[96:97], v[96:97], v[192:193]
	v_pk_mul_f32 v[92:93], v[92:93], v[204:205]
	v_pk_mul_f32 v[88:89], v[88:89], v[200:201]
	v_pk_mul_f32 v[84:85], v[84:85], v[196:197]
	v_pk_mul_f32 v[94:95], v[94:95], v[206:207]
	v_pk_mul_f32 v[90:91], v[90:91], v[202:203]
	v_pk_mul_f32 v[86:87], v[86:87], v[198:199]
	v_pk_mul_f32 v[82:83], v[82:83], v[194:195]
	v_pk_mul_f32 v[80:81], v[80:81], v[192:193]
	v_pk_mul_f32 v[76:77], v[76:77], v[204:205]
	v_pk_mul_f32 v[72:73], v[72:73], v[200:201]
	v_pk_mul_f32 v[68:69], v[68:69], v[196:197]
	v_pk_mul_f32 v[78:79], v[78:79], v[206:207]
	v_pk_mul_f32 v[74:75], v[74:75], v[202:203]
	v_pk_mul_f32 v[70:71], v[70:71], v[198:199]
	v_pk_mul_f32 v[66:67], v[66:67], v[194:195]
	v_pk_mul_f32 v[64:65], v[64:65], v[192:193]
	v_pk_mul_f32 v[60:61], v[60:61], v[204:205]
	v_pk_mul_f32 v[56:57], v[56:57], v[200:201]
	v_pk_mul_f32 v[52:53], v[52:53], v[196:197]
	v_pk_mul_f32 v[62:63], v[62:63], v[206:207]
	v_pk_mul_f32 v[58:59], v[58:59], v[202:203]
	v_pk_mul_f32 v[54:55], v[54:55], v[198:199]
	v_pk_mul_f32 v[50:51], v[50:51], v[194:195]
	v_pk_mul_f32 v[48:49], v[48:49], v[192:193]
	v_pk_mul_f32 v[44:45], v[44:45], v[204:205]
	v_pk_mul_f32 v[40:41], v[40:41], v[200:201]
	v_pk_mul_f32 v[36:37], v[36:37], v[196:197]
	v_pk_mul_f32 v[46:47], v[46:47], v[206:207]
	v_pk_mul_f32 v[42:43], v[42:43], v[202:203]
	v_pk_mul_f32 v[38:39], v[38:39], v[198:199]
	v_pk_mul_f32 v[34:35], v[34:35], v[194:195]
	v_pk_mul_f32 v[32:33], v[32:33], v[192:193]
	v_pk_mul_f32 v[28:29], v[28:29], v[204:205]
	v_pk_mul_f32 v[24:25], v[24:25], v[200:201]
	v_pk_mul_f32 v[20:21], v[20:21], v[196:197]
	v_pk_mul_f32 v[30:31], v[30:31], v[206:207]
	v_pk_mul_f32 v[26:27], v[26:27], v[202:203]
	v_pk_mul_f32 v[22:23], v[22:23], v[198:199]
	v_pk_mul_f32 v[18:19], v[18:19], v[194:195]
	v_pk_mul_f32 v[16:17], v[16:17], v[192:193]

.LBB0_906:
	s_lshl_b32 s4, s80, 14
	v_add3_u32 v236, s4, v221, v220
	ds_read_b128 v[192:195], v236
	ds_read_b128 v[196:199], v236 offset:8192
	v_add3_u32 v236, s4, v222, v220
	ds_read_b128 v[200:203], v236
	ds_read_b128 v[204:207], v236 offset:8192
	v_add3_u32 v236, s4, v223, v220
	ds_read_b128 v[240:243], v236
	ds_read_b128 v[244:247], v236 offset:8192
	v_add3_u32 v236, s4, v225, v220
	ds_read_b128 v[248:251], v236
	ds_read_b128 v[252:255], v236 offset:8192
	s_waitcnt lgkmcnt(7)
	v_mfma_f32_32x32x16_bf16 v[144:159], v[192:195], v[160:163], 0
	v_add3_u32 v236, s4, v226, v220
	ds_read_b128 v[192:195], v236
	s_waitcnt lgkmcnt(7)
	v_mfma_f32_32x32x16_bf16 v[128:143], v[196:199], v[160:163], 0
	ds_read_b128 v[196:199], v236 offset:8192
	s_waitcnt lgkmcnt(7)
	v_mfma_f32_32x32x16_bf16 v[144:159], v[200:203], v[164:167], v[144:159]
	v_add3_u32 v236, s4, v227, v220
	ds_read_b128 v[200:203], v236
	s_waitcnt lgkmcnt(7)
	v_mfma_f32_32x32x16_bf16 v[128:143], v[204:207], v[164:167], v[128:143]
	ds_read_b128 v[204:207], v236 offset:8192
	s_waitcnt lgkmcnt(7)
	v_mfma_f32_32x32x16_bf16 v[144:159], v[240:243], v[168:171], v[144:159]
	v_add3_u32 v236, s4, v228, v220
	ds_read_b128 v[240:243], v236
	s_waitcnt lgkmcnt(7)
	v_mfma_f32_32x32x16_bf16 v[128:143], v[244:247], v[168:171], v[128:143]
	ds_read_b128 v[244:247], v236 offset:8192
	s_waitcnt lgkmcnt(7)
	v_mfma_f32_32x32x16_bf16 v[144:159], v[248:251], v[172:175], v[144:159]
	v_add3_u32 v236, s4, v229, v220
	ds_read_b128 v[248:251], v236
	s_waitcnt lgkmcnt(7)
	v_mfma_f32_32x32x16_bf16 v[128:143], v[252:255], v[172:175], v[128:143]
	ds_read_b128 v[252:255], v236 offset:8192
	s_waitcnt lgkmcnt(7)
	v_mfma_f32_32x32x16_bf16 v[144:159], v[192:195], v[176:179], v[144:159]
	s_waitcnt lgkmcnt(6)
	v_mfma_f32_32x32x16_bf16 v[128:143], v[196:199], v[176:179], v[128:143]
	s_waitcnt lgkmcnt(5)
	v_mfma_f32_32x32x16_bf16 v[144:159], v[200:203], v[180:183], v[144:159]
	s_waitcnt lgkmcnt(4)
	v_mfma_f32_32x32x16_bf16 v[128:143], v[204:207], v[180:183], v[128:143]
	s_waitcnt lgkmcnt(3)
	v_mfma_f32_32x32x16_bf16 v[144:159], v[240:243], v[184:187], v[144:159]
	s_waitcnt lgkmcnt(2)
	v_mfma_f32_32x32x16_bf16 v[128:143], v[244:247], v[184:187], v[128:143]
	s_waitcnt lgkmcnt(1)
	v_mfma_f32_32x32x16_bf16 v[144:159], v[248:251], v[188:191], v[144:159]
	s_waitcnt lgkmcnt(0)
	v_mfma_f32_32x32x16_bf16 v[128:143], v[252:255], v[188:191], v[128:143]
	v_max_f32_e32 v194, v231, v231
	s_nop 9
	v_max_f32_e32 v192, v144, v145
	v_max3_f32 v192, v192, v146, v147
	v_max3_f32 v192, v192, v148, v149
	v_max3_f32 v192, v192, v150, v151
	v_max3_f32 v192, v192, v152, v153
	v_max3_f32 v192, v192, v154, v155
	v_max3_f32 v192, v192, v156, v157
	v_max3_f32 v192, v192, v158, v159
	v_max3_f32 v192, v192, v128, v129
	v_max3_f32 v192, v192, v130, v131
	v_max3_f32 v192, v192, v132, v133
	v_max3_f32 v192, v192, v134, v135
	v_max3_f32 v192, v192, v136, v137
	v_max3_f32 v192, v192, v138, v139
	v_max3_f32 v192, v192, v140, v141
	v_max3_f32 v192, v192, v142, v143
	v_mov_b32_e32 v193, v192
	s_nop 1
	v_permlane32_swap_b32_e32 v192, v193
	v_max_f32_e32 v192, v192, v193
	v_max_f32_e32 v234, v194, v192
	v_sub_f32_e32 v193, v192, v231
	v_sub_f32_e32 v192, v231, v234
	v_mul_f32_e32 v192, 0x3e0293ee, v192
	v_exp_f32_e32 v192, v192
	v_cmp_ge_f32_e32 vcc, s42, v193
	s_cmp_eq_u64 vcc, exec
	s_cselect_b64 s[4:5], -1, 0
	v_cndmask_b32_e64 v233, v192, 1.0, s[4:5]
	v_cmp_gt_f32_e32 vcc, 1.0, v233
	s_cbranch_vccz .LBB0_910
	s_and_saveexec_b64 s[24:25], s[0:1]
	ds_write_b32 v224, v233 offset:128
	s_or_b64 exec, exec, s[24:25]
	s_waitcnt lgkmcnt(0)
	v_add_u32_e32 v192, s21, v210
	ds_read_b128 v[204:207], v192 offset:224
	ds_read_b128 v[200:203], v192 offset:192
	ds_read_b128 v[196:199], v192 offset:160
	ds_read_b128 v[192:195], v192 offset:128
	s_waitcnt lgkmcnt(3)
	v_pk_mul_f32 v[12:13], v[12:13], v[204:205]
	s_waitcnt lgkmcnt(2)
	v_pk_mul_f32 v[8:9], v[8:9], v[200:201]
	s_waitcnt lgkmcnt(1)
	v_pk_mul_f32 v[4:5], v[4:5], v[196:197]
	v_pk_mul_f32 v[14:15], v[14:15], v[206:207]
	v_pk_mul_f32 v[10:11], v[10:11], v[202:203]
	v_pk_mul_f32 v[6:7], v[6:7], v[198:199]
	s_waitcnt lgkmcnt(0)
	v_pk_mul_f32 v[2:3], v[2:3], v[194:195]
	v_pk_mul_f32 v[0:1], v[0:1], v[192:193]
	v_pk_mul_f32 v[124:125], v[124:125], v[204:205]
	v_pk_mul_f32 v[120:121], v[120:121], v[200:201]
	v_pk_mul_f32 v[116:117], v[116:117], v[196:197]
	v_pk_mul_f32 v[126:127], v[126:127], v[206:207]
	v_pk_mul_f32 v[122:123], v[122:123], v[202:203]
	v_pk_mul_f32 v[118:119], v[118:119], v[198:199]
	v_pk_mul_f32 v[114:115], v[114:115], v[194:195]
	v_pk_mul_f32 v[112:113], v[112:113], v[192:193]
	v_pk_mul_f32 v[108:109], v[108:109], v[204:205]
	v_pk_mul_f32 v[104:105], v[104:105], v[200:201]
	v_pk_mul_f32 v[100:101], v[100:101], v[196:197]
	v_pk_mul_f32 v[110:111], v[110:111], v[206:207]
	v_pk_mul_f32 v[106:107], v[106:107], v[202:203]
	v_pk_mul_f32 v[102:103], v[102:103], v[198:199]
	v_pk_mul_f32 v[98:99], v[98:99], v[194:195]
	v_pk_mul_f32 v[96:97], v[96:97], v[192:193]
	v_pk_mul_f32 v[92:93], v[92:93], v[204:205]
	v_pk_mul_f32 v[88:89], v[88:89], v[200:201]
	v_pk_mul_f32 v[84:85], v[84:85], v[196:197]
	v_pk_mul_f32 v[94:95], v[94:95], v[206:207]
	v_pk_mul_f32 v[90:91], v[90:91], v[202:203]
	v_pk_mul_f32 v[86:87], v[86:87], v[198:199]
	v_pk_mul_f32 v[82:83], v[82:83], v[194:195]
	v_pk_mul_f32 v[80:81], v[80:81], v[192:193]
	v_pk_mul_f32 v[76:77], v[76:77], v[204:205]
	v_pk_mul_f32 v[72:73], v[72:73], v[200:201]
	v_pk_mul_f32 v[68:69], v[68:69], v[196:197]
	v_pk_mul_f32 v[78:79], v[78:79], v[206:207]
	v_pk_mul_f32 v[74:75], v[74:75], v[202:203]
	v_pk_mul_f32 v[70:71], v[70:71], v[198:199]
	v_pk_mul_f32 v[66:67], v[66:67], v[194:195]
	v_pk_mul_f32 v[64:65], v[64:65], v[192:193]
	v_pk_mul_f32 v[60:61], v[60:61], v[204:205]
	v_pk_mul_f32 v[56:57], v[56:57], v[200:201]
	v_pk_mul_f32 v[52:53], v[52:53], v[196:197]
	v_pk_mul_f32 v[62:63], v[62:63], v[206:207]
	v_pk_mul_f32 v[58:59], v[58:59], v[202:203]
	v_pk_mul_f32 v[54:55], v[54:55], v[198:199]
	v_pk_mul_f32 v[50:51], v[50:51], v[194:195]
	v_pk_mul_f32 v[48:49], v[48:49], v[192:193]
	v_pk_mul_f32 v[44:45], v[44:45], v[204:205]
	v_pk_mul_f32 v[40:41], v[40:41], v[200:201]
	v_pk_mul_f32 v[36:37], v[36:37], v[196:197]
	v_pk_mul_f32 v[46:47], v[46:47], v[206:207]
	v_pk_mul_f32 v[42:43], v[42:43], v[202:203]
	v_pk_mul_f32 v[38:39], v[38:39], v[198:199]
	v_pk_mul_f32 v[34:35], v[34:35], v[194:195]
	v_pk_mul_f32 v[32:33], v[32:33], v[192:193]
	v_pk_mul_f32 v[28:29], v[28:29], v[204:205]
	v_pk_mul_f32 v[24:25], v[24:25], v[200:201]
	v_pk_mul_f32 v[20:21], v[20:21], v[196:197]
	v_pk_mul_f32 v[30:31], v[30:31], v[206:207]
	v_pk_mul_f32 v[26:27], v[26:27], v[202:203]
	v_pk_mul_f32 v[22:23], v[22:23], v[198:199]
	v_pk_mul_f32 v[18:19], v[18:19], v[194:195]
	v_pk_mul_f32 v[16:17], v[16:17], v[192:193]
